# P3 prologue: relative-bias table loads of a thread issued together (one wait) instead of the serialized load/wait/ds_write loops
# speedup vs baseline: 1.0031x; 1.0031x over previous
.LBB0_249:
	s_andn2_b64 vcc, exec, s[0:1]
	s_cbranch_vccnz .LBB0_360
	v_mov_b32 v2, v0
	v_readlane_b32 s16, v255, 22
	v_readlane_b32 s17, v255, 23
	v_lshlrev_b32_e32 v3, 2, v2
	v_add_u32_e32 v6, 0x1000, v3
	v_add_u32_e32 v9, 0x2000, v3
	s_barrier
	s_nop 1
	global_load_dword v4, v3, s[16:17]
	global_load_dword v5, v3, s[16:17] offset:2048
	global_load_dword v7, v6, s[16:17]
	global_load_dword v8, v6, s[16:17] offset:2048
	v_cmp_gt_u32_e32 vcc, 8, v2
	s_mov_b64 s[0:1], exec
	s_and_b64 exec, exec, vcc
	global_load_dword v10, v9, s[16:17]
	s_mov_b64 exec, s[0:1]
	v_mov_b32_e32 v11, v2
	v_lshrrev_b32_e32 v16, 8, v11
	v_sub_u32_e32 v16, v11, v16
	v_lshrrev_b32_e32 v16, 8, v16
	v_mul_u32_u24_e32 v16, 12, v16
	v_lshl_add_u32 v11, v11, 2, v16
	v_add_u32_e32 v12, 512, v2
	v_lshrrev_b32_e32 v16, 8, v12
	v_sub_u32_e32 v16, v12, v16
	v_lshrrev_b32_e32 v16, 8, v16
	v_mul_u32_u24_e32 v16, 12, v16
	v_lshl_add_u32 v12, v12, 2, v16
	v_add_u32_e32 v13, 1024, v2
	v_lshrrev_b32_e32 v16, 8, v13
	v_sub_u32_e32 v16, v13, v16
	v_lshrrev_b32_e32 v16, 8, v16
	v_mul_u32_u24_e32 v16, 12, v16
	v_lshl_add_u32 v13, v13, 2, v16
	v_add_u32_e32 v14, 1536, v2
	v_lshrrev_b32_e32 v16, 8, v14
	v_sub_u32_e32 v16, v14, v16
	v_lshrrev_b32_e32 v16, 8, v16
	v_mul_u32_u24_e32 v16, 12, v16
	v_lshl_add_u32 v14, v14, 2, v16
	v_add_u32_e32 v15, 2048, v2
	v_lshrrev_b32_e32 v16, 8, v15
	v_sub_u32_e32 v16, v15, v16
	v_lshrrev_b32_e32 v16, 8, v16
	v_mul_u32_u24_e32 v16, 12, v16
	v_lshl_add_u32 v15, v15, 2, v16
	s_waitcnt vmcnt(0)
	v_mul_f32_e32 v4, 0x3fb8aa3b, v4
	ds_write_b32 v11, v4
	v_mul_f32_e32 v5, 0x3fb8aa3b, v5
	ds_write_b32 v12, v5
	v_mul_f32_e32 v7, 0x3fb8aa3b, v7
	ds_write_b32 v13, v7
	v_mul_f32_e32 v8, 0x3fb8aa3b, v8
	ds_write_b32 v14, v8
	s_and_b64 exec, exec, vcc
	v_mul_f32_e32 v10, 0x3fb8aa3b, v10
	ds_write_b32 v15, v10
	s_mov_b64 exec, s[0:1]
